# bf16 GEMM epilogues (in-proj, FFN1): 16-piece store ladder with 8 image reads in flight, counted waits, running 64-bit row pointer instead of per-piece 64-bit multiply
# speedup vs baseline: 1.0018x; 1.0018x over previous
; DI unsigned pk2(float a, float b) { f32x2 v = {a, b}; return __builtin_bit_cast(unsigned, __builtin_convertvector(v, bf16x2_t)); }
;   DI static float act(float v) { const float t = fmaxf(v, 0.f); return t * t; }
; #define H_LOAD(KT) do { _Pragma("unroll") for (int i = 0; i < 4; ++i) { ra[i] = *(const u32x4*)(Ap + (size_t)i * 64 * K + (KT) * 64); rb[i] = *(const u32x4*)(Bp + (size_t)i * 64 * K + (KT) * 64); } } while (0)
; template <class Epi>
; DI void gemm_phase512(const bf16_t* A, const bf16_t* Bt, int mtiles, int ntiles, int K, int Kper, int ksplit, const Epi& epi,
;                       unsigned char* smem, int bid, int nb) {
;     ...
;     const int itn = it + nb;
;     const bool more = itn < total;
;     int pmn = pm, pnn = pn; const bf16_t* Apn = Ap; const bf16_t* Bpn = Bp;
;     if (more) H_TILE(itn, pmn, pnn, Apn, Bpn);
;     const int pm_cur = pm, pn_cur = pn;
;     Ap = Apn; Bp = Bpn;
;     H_LOAD(0);
;     {
;       unsigned char* wl = smem + wave * 18432;
;       const int m0 = pm_cur * 256 + wm * 128, n0 = pn_cur * 256 + wn * 64;
;       if constexpr (Epi::kBf16) {
; #pragma unroll
;         for (int ni = 0; ni < 2; ++ni)
; #pragma unroll
;           for (int mi = 0; mi < 4; ++mi)
; #pragma unroll
;             for (int g = 0; g < 4; ++g) {
;               u32x2 w;
;               w[0] = pk2(Epi::act(acc[ni][mi][4 * g]), Epi::act(acc[ni][mi][4 * g + 1]));
;               w[1] = pk2(Epi::act(acc[ni][mi][4 * g + 2]), Epi::act(acc[ni][mi][4 * g + 3]));
;               *(u32x2*)(wl + (mi * 32 + l31) * LDS_STRIDE + (ni * 32 + 8 * g + 4 * hh) * 2) = w;
;             }
;         asm volatile("" ::: "memory");
; #pragma unroll
;         for (int i = 0; i < 16; ++i) {
;           const int row = (lane >> 3) + 8 * i, ch = lane & 7;
;           const u32x4 w = *(const u32x4*)(wl + row * LDS_STRIDE + ch * 16);
;           *(u32x4*)(epi.O + (size_t)(m0 + row) * epi.ldc + n0 + ch * 8) = w;
.LBB0_126:
	s_waitcnt vmcnt(5)
	v_add_co_u32_e32 v132, vcc, 0x20000, v160
	global_load_dwordx4 v[128:131], v[160:161], off
	s_nop 0
	v_addc_co_u32_e32 v133, vcc, 0, v161, vcc
	s_waitcnt vmcnt(5)
	v_add_co_u32_e32 v136, vcc, 0x20000, v170
	global_load_dwordx4 v[132:135], v[132:133], off
	s_nop 0
	v_addc_co_u32_e32 v137, vcc, 0, v171, vcc
	s_waitcnt vmcnt(5)
	v_add_co_u32_e32 v140, vcc, 0x40000, v160
	global_load_dwordx4 v[136:139], v[136:137], off
	s_nop 0
	v_addc_co_u32_e32 v141, vcc, 0, v161, vcc
	s_waitcnt vmcnt(5)
	v_add_co_u32_e32 v144, vcc, 0x40000, v170
	global_load_dwordx4 v[140:143], v[140:141], off
	s_nop 0
	v_addc_co_u32_e32 v145, vcc, 0, v171, vcc
	v_add_co_u32_e32 v148, vcc, 0x60000, v160
	global_load_dwordx4 v[144:147], v[144:145], off
	s_nop 0
	v_addc_co_u32_e32 v149, vcc, 0, v161, vcc
	s_waitcnt vmcnt(6)
	v_add_co_u32_e32 v152, vcc, 0x60000, v170
	global_load_dwordx4 v[148:151], v[148:149], off
	s_nop 0
	v_addc_co_u32_e32 v153, vcc, 0, v171, vcc
	global_load_dwordx4 v[156:159], v[170:171], off
	s_nop 0
	global_load_dwordx4 v[152:155], v[152:153], off
	v_cvt_pk_bf16_f32 v112, v112, v113
	v_cvt_pk_bf16_f32 v113, v114, v115
	v_cvt_pk_bf16_f32 v114, v116, v117
	v_cvt_pk_bf16_f32 v115, v118, v119
	v_cvt_pk_bf16_f32 v96, v96, v97
	v_cvt_pk_bf16_f32 v97, v98, v99
	v_cvt_pk_bf16_f32 v98, v100, v101
	v_cvt_pk_bf16_f32 v99, v102, v103
	v_add_u32_e32 v100, 0x1000, v197
	v_cvt_pk_bf16_f32 v80, v80, v81
	v_cvt_pk_bf16_f32 v81, v82, v83
	v_cvt_pk_bf16_f32 v82, v84, v85
	v_cvt_pk_bf16_f32 v83, v86, v87
	v_add_u32_e32 v84, 0x2000, v197
	v_cvt_pk_bf16_f32 v64, v64, v65
	v_cvt_pk_bf16_f32 v65, v66, v67
	v_cvt_pk_bf16_f32 v66, v68, v69
	v_cvt_pk_bf16_f32 v67, v70, v71
	v_add_u32_e32 v68, 0x3000, v197
	v_cvt_pk_bf16_f32 v48, v48, v49
	v_cvt_pk_bf16_f32 v49, v50, v51
	v_cvt_pk_bf16_f32 v50, v52, v53
	v_cvt_pk_bf16_f32 v51, v54, v55
	v_cvt_pk_bf16_f32 v32, v32, v33
	v_cvt_pk_bf16_f32 v33, v34, v35
	v_cvt_pk_bf16_f32 v34, v36, v37
	v_cvt_pk_bf16_f32 v35, v38, v39
	v_cvt_pk_bf16_f32 v16, v16, v17
	v_cvt_pk_bf16_f32 v17, v18, v19
	v_cvt_pk_bf16_f32 v18, v20, v21
	v_cvt_pk_bf16_f32 v19, v22, v23
	v_cvt_pk_bf16_f32 v0, v0, v1
	v_cvt_pk_bf16_f32 v1, v2, v3
	v_cvt_pk_bf16_f32 v2, v4, v5
	v_cvt_pk_bf16_f32 v3, v6, v7
	ds_write2_b64 v197, v[112:113], v[114:115] offset1:2
	v_cvt_pk_bf16_f32 v112, v120, v121
	v_cvt_pk_bf16_f32 v113, v122, v123
	v_cvt_pk_bf16_f32 v114, v124, v125
	v_cvt_pk_bf16_f32 v115, v126, v127
	ds_write2_b64 v100, v[96:97], v[98:99] offset0:64 offset1:66
	v_cvt_pk_bf16_f32 v96, v104, v105
	v_cvt_pk_bf16_f32 v97, v106, v107
	v_cvt_pk_bf16_f32 v98, v108, v109
	v_cvt_pk_bf16_f32 v99, v110, v111
	ds_write2_b64 v84, v[80:81], v[82:83] offset0:128 offset1:130
	v_cvt_pk_bf16_f32 v80, v88, v89
	v_cvt_pk_bf16_f32 v81, v90, v91
	v_cvt_pk_bf16_f32 v82, v92, v93
	v_cvt_pk_bf16_f32 v83, v94, v95
	ds_write2_b64 v68, v[64:65], v[66:67] offset0:192 offset1:194
	v_cvt_pk_bf16_f32 v64, v72, v73
	v_cvt_pk_bf16_f32 v65, v74, v75
	v_cvt_pk_bf16_f32 v66, v76, v77
	v_cvt_pk_bf16_f32 v67, v78, v79
	ds_write2_b64 v197, v[48:49], v[50:51] offset0:8 offset1:10
	v_cvt_pk_bf16_f32 v48, v56, v57
	v_cvt_pk_bf16_f32 v49, v58, v59
	v_cvt_pk_bf16_f32 v50, v60, v61
	v_cvt_pk_bf16_f32 v51, v62, v63
	ds_write2_b64 v100, v[32:33], v[34:35] offset0:72 offset1:74
	v_cvt_pk_bf16_f32 v32, v40, v41
	v_cvt_pk_bf16_f32 v33, v42, v43
	v_cvt_pk_bf16_f32 v34, v44, v45
	v_cvt_pk_bf16_f32 v35, v46, v47
	ds_write2_b64 v84, v[16:17], v[18:19] offset0:136 offset1:138
	v_cvt_pk_bf16_f32 v16, v24, v25
	v_cvt_pk_bf16_f32 v17, v26, v27
	v_cvt_pk_bf16_f32 v18, v28, v29
	v_cvt_pk_bf16_f32 v19, v30, v31
	ds_write2_b64 v68, v[0:1], v[2:3] offset0:200 offset1:202
	v_cvt_pk_bf16_f32 v0, v8, v9
	v_cvt_pk_bf16_f32 v1, v10, v11
	v_cvt_pk_bf16_f32 v2, v12, v13
	v_cvt_pk_bf16_f32 v3, v14, v15
	ds_write2_b64 v197, v[112:113], v[114:115] offset0:4 offset1:6
	ds_write2_b64 v100, v[96:97], v[98:99] offset0:68 offset1:70
	ds_write2_b64 v84, v[80:81], v[82:83] offset0:132 offset1:134
	ds_write2_b64 v68, v[64:65], v[66:67] offset0:196 offset1:198
	ds_write2_b64 v197, v[48:49], v[50:51] offset0:12 offset1:14
	ds_write2_b64 v100, v[32:33], v[34:35] offset0:76 offset1:78
	ds_write2_b64 v84, v[16:17], v[18:19] offset0:140 offset1:142
	ds_write2_b64 v68, v[0:1], v[2:3] offset0:204 offset1:206
	v_lshl_add_u32 v0, s24, 8, v173
	v_ashrrev_i32_e32 v1, 31, v0
	v_lshl_or_b32 v12, s25, 8, v174
	v_lshl_add_u64 v[8:9], v[0:1], 1, v[166:167]
	v_or_b32_e32 v4, v12, v175
	v_mad_i64_i32 v[10:11], s[24:25], v4, s20, v[8:9]
	s_mov_b32 s100, 0xd000
	s_mov_b32 s101, 0
	ds_read_b128 v[16:19], v198
	ds_read_b128 v[20:23], v198 offset:1152
	ds_read_b128 v[24:27], v198 offset:2304
	ds_read_b128 v[28:31], v198 offset:3456
	ds_read_b128 v[32:35], v198 offset:4608
	ds_read_b128 v[36:39], v198 offset:5760
	ds_read_b128 v[40:43], v198 offset:6912
	ds_read_b128 v[44:47], v198 offset:8064
	s_waitcnt lgkmcnt(7)
; template <class Epi>
; DI void gemm_phase512(const bf16_t* A, const bf16_t* Bt, int mtiles, int ntiles, int K, int Kper, int ksplit, const Epi& epi,
;                       unsigned char* smem, int bid, int nb) {
;     ...
; #pragma unroll
;         for (int i = 0; i < 16; ++i) {
;           const int row = (lane >> 3) + 8 * i, ch = lane & 7;
;           const u32x4 w = *(const u32x4*)(wl + row * LDS_STRIDE + ch * 16);
;           *(u32x4*)(epi.O + (size_t)(m0 + row) * epi.ldc + n0 + ch * 8) = w;
;         }
	global_store_dwordx4 v[10:11], v[16:19], off
	v_lshl_add_u64 v[10:11], v[10:11], 0, s[100:101]
	ds_read_b128 v[48:51], v198 offset:9216
	s_waitcnt lgkmcnt(7)
	global_store_dwordx4 v[10:11], v[20:23], off
	v_lshl_add_u64 v[10:11], v[10:11], 0, s[100:101]
	ds_read_b128 v[52:55], v198 offset:10368
	s_waitcnt lgkmcnt(7)
	global_store_dwordx4 v[10:11], v[24:27], off
	v_lshl_add_u64 v[10:11], v[10:11], 0, s[100:101]
	ds_read_b128 v[56:59], v198 offset:11520
	s_waitcnt lgkmcnt(7)
	global_store_dwordx4 v[10:11], v[28:31], off
	v_lshl_add_u64 v[10:11], v[10:11], 0, s[100:101]
	ds_read_b128 v[60:63], v198 offset:12672
	s_waitcnt lgkmcnt(7)
	global_store_dwordx4 v[10:11], v[32:35], off
	v_lshl_add_u64 v[10:11], v[10:11], 0, s[100:101]
	ds_read_b128 v[64:67], v198 offset:13824
	s_waitcnt lgkmcnt(7)
	global_store_dwordx4 v[10:11], v[36:39], off
	v_lshl_add_u64 v[10:11], v[10:11], 0, s[100:101]
	ds_read_b128 v[68:71], v198 offset:14976
	s_waitcnt lgkmcnt(7)
	global_store_dwordx4 v[10:11], v[40:43], off
	v_lshl_add_u64 v[10:11], v[10:11], 0, s[100:101]
	ds_read_b128 v[72:75], v198 offset:16128
	s_waitcnt lgkmcnt(7)
	global_store_dwordx4 v[10:11], v[44:47], off
	v_lshl_add_u64 v[10:11], v[10:11], 0, s[100:101]
	ds_read_b128 v[76:79], v198 offset:17280
	s_waitcnt lgkmcnt(7)
	global_store_dwordx4 v[10:11], v[48:51], off
	v_lshl_add_u64 v[10:11], v[10:11], 0, s[100:101]
	s_waitcnt lgkmcnt(6)
	global_store_dwordx4 v[10:11], v[52:55], off
	v_lshl_add_u64 v[10:11], v[10:11], 0, s[100:101]
	s_waitcnt lgkmcnt(5)
	global_store_dwordx4 v[10:11], v[56:59], off
	v_lshl_add_u64 v[10:11], v[10:11], 0, s[100:101]
	s_waitcnt lgkmcnt(4)
	global_store_dwordx4 v[10:11], v[60:63], off
	v_lshl_add_u64 v[10:11], v[10:11], 0, s[100:101]
	s_waitcnt lgkmcnt(3)
	global_store_dwordx4 v[10:11], v[64:67], off
	v_lshl_add_u64 v[10:11], v[10:11], 0, s[100:101]
	s_waitcnt lgkmcnt(2)
	global_store_dwordx4 v[10:11], v[68:71], off
	v_lshl_add_u64 v[10:11], v[10:11], 0, s[100:101]
	s_waitcnt lgkmcnt(1)
	global_store_dwordx4 v[10:11], v[72:75], off
	v_lshl_add_u64 v[10:11], v[10:11], 0, s[100:101]
	s_waitcnt lgkmcnt(0)
	global_store_dwordx4 v[10:11], v[76:79], off
	s_andn2_b64 vcc, exec, s[2:3]
	s_mov_b32 s24, s22
	s_mov_b32 s25, s26
	s_barrier
	s_cbranch_vccz .LBB0_131

; DI unsigned pk2(float a, float b) { f32x2 v = {a, b}; return __builtin_bit_cast(unsigned, __builtin_convertvector(v, bf16x2_t)); }
;   DI static float act(float v) { const float t = fmaxf(v, 0.f); return t * t; }
; template <class Epi>
; DI void gemm_phase512(const bf16_t* A, const bf16_t* Bt, int mtiles, int ntiles, int K, int Kper, int ksplit, const Epi& epi,
;                       unsigned char* smem, int bid, int nb) {
;     ...
;         for (int ni = 0; ni < 2; ++ni)
; #pragma unroll
;           for (int mi = 0; mi < 4; ++mi)
; #pragma unroll
;             for (int g = 0; g < 4; ++g) {
;               u32x2 w;
;               w[0] = pk2(Epi::act(acc[ni][mi][4 * g]), Epi::act(acc[ni][mi][4 * g + 1]));
;               w[1] = pk2(Epi::act(acc[ni][mi][4 * g + 2]), Epi::act(acc[ni][mi][4 * g + 3]));
;               *(u32x2*)(wl + (mi * 32 + l31) * LDS_STRIDE + (ni * 32 + 8 * g + 4 * hh) * 2) = w;
;             }
.LBB0_702:
	v_max_f32_e32 v112, v112, v112
	v_max_f32_e32 v113, v113, v113
	v_max_f32_e32 v96, v96, v96
	v_max_f32_e32 v97, v97, v97
	v_max_f32_e32 v80, v80, v80
	v_max_f32_e32 v81, v81, v81
	v_max_f32_e32 v64, v64, v64
	v_max_f32_e32 v65, v65, v65
	v_max_f32_e32 v48, v48, v48
	v_max_f32_e32 v49, v49, v49
	v_max_f32_e32 v32, v32, v32
	v_max_f32_e32 v33, v33, v33
	v_max_f32_e32 v16, v16, v16
	v_max_f32_e32 v17, v17, v17
	v_max_f32_e32 v0, v0, v0
	v_max_f32_e32 v1, v1, v1
	v_max_f32_e32 v112, 0, v112
	v_max_f32_e32 v113, 0, v113
	v_max_f32_e32 v96, 0, v96
	v_max_f32_e32 v97, 0, v97
	v_max_f32_e32 v80, 0, v80
	v_max_f32_e32 v81, 0, v81
	v_max_f32_e32 v64, 0, v64
	v_max_f32_e32 v65, 0, v65
	v_max_f32_e32 v48, 0, v48
	v_max_f32_e32 v49, 0, v49
	v_max_f32_e32 v32, 0, v32
	v_max_f32_e32 v33, 0, v33
	v_max_f32_e32 v16, 0, v16
	v_max_f32_e32 v17, 0, v17
	v_max_f32_e32 v0, 0, v0
	v_max_f32_e32 v1, 0, v1
	v_pk_mul_f32 v[112:113], v[112:113], v[112:113]
	v_pk_mul_f32 v[96:97], v[96:97], v[96:97]
	v_pk_mul_f32 v[80:81], v[80:81], v[80:81]
	v_pk_mul_f32 v[64:65], v[64:65], v[64:65]
	v_pk_mul_f32 v[48:49], v[48:49], v[48:49]
	v_pk_mul_f32 v[32:33], v[32:33], v[32:33]
	v_pk_mul_f32 v[16:17], v[16:17], v[16:17]
	v_pk_mul_f32 v[0:1], v[0:1], v[0:1]
	s_waitcnt vmcnt(5)
	v_add_co_u32_e32 v132, vcc, 0x20000, v164
	v_cvt_pk_bf16_f32 v112, v112, v113
	v_max_f32_e32 v113, v114, v114
	v_cvt_pk_bf16_f32 v96, v96, v97
	v_max_f32_e32 v97, v98, v98
	v_cvt_pk_bf16_f32 v80, v80, v81
	v_max_f32_e32 v81, v82, v82
	v_cvt_pk_bf16_f32 v64, v64, v65
	v_max_f32_e32 v65, v66, v66
	v_cvt_pk_bf16_f32 v48, v48, v49
	v_max_f32_e32 v49, v50, v50
	v_cvt_pk_bf16_f32 v32, v32, v33
	v_max_f32_e32 v33, v34, v34
	v_cvt_pk_bf16_f32 v16, v16, v17
	v_max_f32_e32 v17, v18, v18
	v_cvt_pk_bf16_f32 v0, v0, v1
	v_max_f32_e32 v1, v2, v2
	v_addc_co_u32_e32 v133, vcc, 0, v165, vcc
	v_max_f32_e32 v114, 0, v113
	v_max_f32_e32 v113, v115, v115
	v_max_f32_e32 v98, 0, v97
	v_max_f32_e32 v97, v99, v99
	v_max_f32_e32 v82, 0, v81
	v_max_f32_e32 v81, v83, v83
	v_max_f32_e32 v66, 0, v65
	v_max_f32_e32 v65, v67, v67
	v_max_f32_e32 v50, 0, v49
	v_max_f32_e32 v49, v51, v51
	v_max_f32_e32 v34, 0, v33
	v_max_f32_e32 v33, v35, v35
	v_max_f32_e32 v18, 0, v17
	v_max_f32_e32 v17, v19, v19
	v_max_f32_e32 v2, 0, v1
	v_max_f32_e32 v1, v3, v3
	s_waitcnt vmcnt(4)
	v_add_co_u32_e32 v136, vcc, 0x20000, v170
	v_max_f32_e32 v115, 0, v113
	v_max_f32_e32 v99, 0, v97
	v_max_f32_e32 v83, 0, v81
	v_max_f32_e32 v67, 0, v65
	v_max_f32_e32 v51, 0, v49
	v_max_f32_e32 v35, 0, v33
	v_max_f32_e32 v19, 0, v17
	v_max_f32_e32 v3, 0, v1
	v_addc_co_u32_e32 v137, vcc, 0, v171, vcc
	v_pk_mul_f32 v[114:115], v[114:115], v[114:115]
	v_pk_mul_f32 v[98:99], v[98:99], v[98:99]
	v_pk_mul_f32 v[82:83], v[82:83], v[82:83]
	v_pk_mul_f32 v[66:67], v[66:67], v[66:67]
	v_pk_mul_f32 v[50:51], v[50:51], v[50:51]
	v_pk_mul_f32 v[34:35], v[34:35], v[34:35]
	v_pk_mul_f32 v[18:19], v[18:19], v[18:19]
	v_pk_mul_f32 v[2:3], v[2:3], v[2:3]
	s_waitcnt vmcnt(3)
	v_add_co_u32_e32 v140, vcc, 0x40000, v164
	v_cvt_pk_bf16_f32 v113, v114, v115
	v_max_f32_e32 v114, v116, v116
	v_max_f32_e32 v115, v117, v117
	v_cvt_pk_bf16_f32 v97, v98, v99
	v_max_f32_e32 v98, v100, v100
	v_max_f32_e32 v99, v101, v101
	v_cvt_pk_bf16_f32 v81, v82, v83
	v_max_f32_e32 v82, v84, v84
	v_max_f32_e32 v83, v85, v85
	v_cvt_pk_bf16_f32 v65, v66, v67
	v_max_f32_e32 v66, v68, v68
	v_max_f32_e32 v67, v69, v69
	v_cvt_pk_bf16_f32 v49, v50, v51
	v_max_f32_e32 v50, v52, v52
	v_max_f32_e32 v51, v53, v53
	v_cvt_pk_bf16_f32 v33, v34, v35
	v_max_f32_e32 v34, v36, v36
	v_max_f32_e32 v35, v37, v37
	v_cvt_pk_bf16_f32 v17, v18, v19
	v_max_f32_e32 v18, v20, v20
	v_max_f32_e32 v19, v21, v21
	v_cvt_pk_bf16_f32 v1, v2, v3
	v_max_f32_e32 v2, v4, v4
	v_max_f32_e32 v3, v5, v5
	v_addc_co_u32_e32 v141, vcc, 0, v165, vcc
	v_max_f32_e32 v114, 0, v114
	v_max_f32_e32 v115, 0, v115
	v_max_f32_e32 v98, 0, v98
	v_max_f32_e32 v99, 0, v99
	v_max_f32_e32 v82, 0, v82
	v_max_f32_e32 v83, 0, v83
	v_max_f32_e32 v66, 0, v66
	v_max_f32_e32 v67, 0, v67
	v_max_f32_e32 v50, 0, v50
	v_max_f32_e32 v51, 0, v51
	v_max_f32_e32 v34, 0, v34
	v_max_f32_e32 v35, 0, v35
	v_max_f32_e32 v18, 0, v18
	v_max_f32_e32 v19, 0, v19
	v_max_f32_e32 v2, 0, v2
	v_max_f32_e32 v3, 0, v3
	s_waitcnt vmcnt(2)
	v_add_co_u32_e32 v144, vcc, 0x40000, v170
	v_pk_mul_f32 v[114:115], v[114:115], v[114:115]
	v_pk_mul_f32 v[98:99], v[98:99], v[98:99]
	v_pk_mul_f32 v[82:83], v[82:83], v[82:83]
	v_pk_mul_f32 v[66:67], v[66:67], v[66:67]
	v_pk_mul_f32 v[50:51], v[50:51], v[50:51]
	v_pk_mul_f32 v[34:35], v[34:35], v[34:35]
	v_pk_mul_f32 v[18:19], v[18:19], v[18:19]
	v_pk_mul_f32 v[2:3], v[2:3], v[2:3]
	v_addc_co_u32_e32 v145, vcc, 0, v171, vcc
	v_cvt_pk_bf16_f32 v114, v114, v115
	v_max_f32_e32 v115, v118, v118
	v_cvt_pk_bf16_f32 v98, v98, v99
	v_max_f32_e32 v99, v102, v102
	v_cvt_pk_bf16_f32 v82, v82, v83
	v_max_f32_e32 v83, v86, v86
	v_cvt_pk_bf16_f32 v66, v66, v67
	v_max_f32_e32 v67, v70, v70
	v_cvt_pk_bf16_f32 v50, v50, v51
	v_max_f32_e32 v51, v54, v54
	v_cvt_pk_bf16_f32 v34, v34, v35
	v_max_f32_e32 v35, v38, v38
	v_cvt_pk_bf16_f32 v18, v18, v19
	v_max_f32_e32 v19, v22, v22
	v_cvt_pk_bf16_f32 v2, v2, v3
	v_max_f32_e32 v3, v6, v6
	v_add_co_u32_e32 v148, vcc, 0x60000, v164
	v_max_f32_e32 v116, 0, v115
	v_max_f32_e32 v115, v119, v119
	v_max_f32_e32 v100, 0, v99
	v_max_f32_e32 v99, v103, v103
	v_max_f32_e32 v84, 0, v83
	v_max_f32_e32 v83, v87, v87
	v_max_f32_e32 v68, 0, v67
	v_max_f32_e32 v67, v71, v71
	v_max_f32_e32 v52, 0, v51
	v_max_f32_e32 v51, v55, v55
	v_max_f32_e32 v36, 0, v35
	v_max_f32_e32 v35, v39, v39
	v_max_f32_e32 v20, 0, v19
	v_max_f32_e32 v19, v23, v23
	v_max_f32_e32 v4, 0, v3
	v_max_f32_e32 v3, v7, v7
	v_addc_co_u32_e32 v149, vcc, 0, v165, vcc
	v_max_f32_e32 v117, 0, v115
	v_max_f32_e32 v101, 0, v99
	v_max_f32_e32 v85, 0, v83
	v_max_f32_e32 v69, 0, v67
	v_max_f32_e32 v53, 0, v51
	v_max_f32_e32 v37, 0, v35
	v_max_f32_e32 v21, 0, v19
	v_max_f32_e32 v5, 0, v3
	s_waitcnt vmcnt(1)
; DI unsigned pk2(float a, float b) { f32x2 v = {a, b}; return __builtin_bit_cast(unsigned, __builtin_convertvector(v, bf16x2_t)); }
; #define H_LOAD(KT) do { _Pragma("unroll") for (int i = 0; i < 4; ++i) { ra[i] = *(const u32x4*)(Ap + (size_t)i * 64 * K + (KT) * 64); rb[i] = *(const u32x4*)(Bp + (size_t)i * 64 * K + (KT) * 64); } } while (0)
;   DI static float act(float v) { const float t = fmaxf(v, 0.f); return t * t; }
; template <class Epi>
; DI void gemm_phase512(const bf16_t* A, const bf16_t* Bt, int mtiles, int ntiles, int K, int Kper, int ksplit, const Epi& epi,
;                       unsigned char* smem, int bid, int nb) {
;     ...
;     H_LOAD(0);
;     {
;       unsigned char* wl = smem + wave * 18432;
;       const int m0 = pm_cur * 256 + wm * 128, n0 = pn_cur * 256 + wn * 64;
;       if constexpr (Epi::kBf16) {
; #pragma unroll
;         for (int ni = 0; ni < 2; ++ni)
; #pragma unroll
;           for (int mi = 0; mi < 4; ++mi)
; #pragma unroll
;             for (int g = 0; g < 4; ++g) {
;               u32x2 w;
;               w[0] = pk2(Epi::act(acc[ni][mi][4 * g]), Epi::act(acc[ni][mi][4 * g + 1]));
;               w[1] = pk2(Epi::act(acc[ni][mi][4 * g + 2]), Epi::act(acc[ni][mi][4 * g + 3]));
;               *(u32x2*)(wl + (mi * 32 + l31) * LDS_STRIDE + (ni * 32 + 8 * g + 4 * hh) * 2) = w;
;             }
	v_add_co_u32_e32 v152, vcc, 0x60000, v170
	v_pk_mul_f32 v[116:117], v[116:117], v[116:117]
	v_pk_mul_f32 v[100:101], v[100:101], v[100:101]
	v_pk_mul_f32 v[84:85], v[84:85], v[84:85]
	v_pk_mul_f32 v[68:69], v[68:69], v[68:69]
	v_pk_mul_f32 v[52:53], v[52:53], v[52:53]
	v_pk_mul_f32 v[36:37], v[36:37], v[36:37]
	v_pk_mul_f32 v[20:21], v[20:21], v[20:21]
	v_pk_mul_f32 v[4:5], v[4:5], v[4:5]
	v_addc_co_u32_e32 v153, vcc, 0, v171, vcc
	v_cvt_pk_bf16_f32 v115, v116, v117
	v_cvt_pk_bf16_f32 v99, v100, v101
	v_add_u32_e32 v102, 0x1000, v197
	v_cvt_pk_bf16_f32 v83, v84, v85
	v_add_u32_e32 v86, 0x2000, v197
	v_cvt_pk_bf16_f32 v67, v68, v69
	v_add_u32_e32 v70, 0x3000, v197
	v_cvt_pk_bf16_f32 v51, v52, v53
	v_cvt_pk_bf16_f32 v35, v36, v37
	v_cvt_pk_bf16_f32 v19, v20, v21
	v_cvt_pk_bf16_f32 v3, v4, v5
	global_load_dwordx4 v[128:131], v[164:165], off
	s_andn2_b64 vcc, exec, s[2:3]
	global_load_dwordx4 v[132:135], v[132:133], off
	s_nop 0
	global_load_dwordx4 v[136:139], v[136:137], off
	s_nop 0
	global_load_dwordx4 v[140:143], v[140:141], off
	s_nop 0
	global_load_dwordx4 v[144:147], v[144:145], off
	s_nop 0
	global_load_dwordx4 v[148:151], v[148:149], off
	s_nop 0
	global_load_dwordx4 v[156:159], v[170:171], off
	s_nop 0
	global_load_dwordx4 v[152:155], v[152:153], off
	ds_write2_b64 v197, v[112:113], v[114:115] offset1:2
	v_max_f32_e32 v112, v120, v120
	v_max_f32_e32 v113, v121, v121
	ds_write2_b64 v102, v[96:97], v[98:99] offset0:64 offset1:66
	v_max_f32_e32 v96, v104, v104
	v_max_f32_e32 v97, v105, v105
	ds_write2_b64 v86, v[80:81], v[82:83] offset0:128 offset1:130
	v_max_f32_e32 v80, v88, v88
	v_max_f32_e32 v81, v89, v89
	ds_write2_b64 v70, v[64:65], v[66:67] offset0:192 offset1:194
	v_max_f32_e32 v64, v72, v72
	v_max_f32_e32 v65, v73, v73
	ds_write2_b64 v197, v[48:49], v[50:51] offset0:8 offset1:10
	v_max_f32_e32 v48, v56, v56
	v_max_f32_e32 v49, v57, v57
	ds_write2_b64 v102, v[32:33], v[34:35] offset0:72 offset1:74
	v_max_f32_e32 v32, v40, v40
	v_max_f32_e32 v33, v41, v41
	ds_write2_b64 v86, v[16:17], v[18:19] offset0:136 offset1:138
	v_max_f32_e32 v16, v24, v24
	v_max_f32_e32 v17, v25, v25
	ds_write2_b64 v70, v[0:1], v[2:3] offset0:200 offset1:202
	v_max_f32_e32 v0, v8, v8
	v_max_f32_e32 v1, v9, v9
	v_max_f32_e32 v112, 0, v112
	v_max_f32_e32 v113, 0, v113
	v_max_f32_e32 v96, 0, v96
	v_max_f32_e32 v97, 0, v97
	v_max_f32_e32 v80, 0, v80
	v_max_f32_e32 v81, 0, v81
	v_max_f32_e32 v64, 0, v64
	v_max_f32_e32 v65, 0, v65
	v_max_f32_e32 v48, 0, v48
	v_max_f32_e32 v49, 0, v49
	v_max_f32_e32 v32, 0, v32
	v_max_f32_e32 v33, 0, v33
	v_max_f32_e32 v16, 0, v16
	v_max_f32_e32 v17, 0, v17
	v_max_f32_e32 v0, 0, v0
	v_max_f32_e32 v1, 0, v1
	v_pk_mul_f32 v[112:113], v[112:113], v[112:113]
	v_pk_mul_f32 v[96:97], v[96:97], v[96:97]
	v_pk_mul_f32 v[80:81], v[80:81], v[80:81]
	v_pk_mul_f32 v[64:65], v[64:65], v[64:65]
	v_pk_mul_f32 v[48:49], v[48:49], v[48:49]
	v_pk_mul_f32 v[32:33], v[32:33], v[32:33]
	v_pk_mul_f32 v[16:17], v[16:17], v[16:17]
	v_pk_mul_f32 v[0:1], v[0:1], v[0:1]
	v_cvt_pk_bf16_f32 v112, v112, v113
	v_max_f32_e32 v113, v122, v122
	v_cvt_pk_bf16_f32 v96, v96, v97
	v_max_f32_e32 v97, v106, v106
	v_cvt_pk_bf16_f32 v80, v80, v81
	v_max_f32_e32 v81, v90, v90
	v_cvt_pk_bf16_f32 v64, v64, v65
	v_max_f32_e32 v65, v74, v74
	v_cvt_pk_bf16_f32 v48, v48, v49
	v_max_f32_e32 v49, v58, v58
	v_cvt_pk_bf16_f32 v32, v32, v33
	v_max_f32_e32 v33, v42, v42
	v_cvt_pk_bf16_f32 v16, v16, v17
	v_max_f32_e32 v17, v26, v26
	v_cvt_pk_bf16_f32 v0, v0, v1
	v_max_f32_e32 v1, v10, v10
	v_max_f32_e32 v114, 0, v113
	v_max_f32_e32 v113, v123, v123
	v_max_f32_e32 v98, 0, v97
	v_max_f32_e32 v97, v107, v107
	v_max_f32_e32 v82, 0, v81
	v_max_f32_e32 v81, v91, v91
	v_max_f32_e32 v66, 0, v65
	v_max_f32_e32 v65, v75, v75
	v_max_f32_e32 v50, 0, v49
	v_max_f32_e32 v49, v59, v59
	v_max_f32_e32 v34, 0, v33
	v_max_f32_e32 v33, v43, v43
	v_max_f32_e32 v18, 0, v17
	v_max_f32_e32 v17, v27, v27
	v_max_f32_e32 v2, 0, v1
	v_max_f32_e32 v1, v11, v11
	v_max_f32_e32 v115, 0, v113
	v_max_f32_e32 v99, 0, v97
	v_max_f32_e32 v83, 0, v81
	v_max_f32_e32 v67, 0, v65
	v_max_f32_e32 v51, 0, v49
	v_max_f32_e32 v35, 0, v33
	v_max_f32_e32 v19, 0, v17
	v_max_f32_e32 v3, 0, v1
	v_pk_mul_f32 v[114:115], v[114:115], v[114:115]
	v_pk_mul_f32 v[98:99], v[98:99], v[98:99]
	v_pk_mul_f32 v[82:83], v[82:83], v[82:83]
	v_pk_mul_f32 v[66:67], v[66:67], v[66:67]
	v_pk_mul_f32 v[50:51], v[50:51], v[50:51]
	v_pk_mul_f32 v[34:35], v[34:35], v[34:35]
	v_pk_mul_f32 v[18:19], v[18:19], v[18:19]
	v_pk_mul_f32 v[2:3], v[2:3], v[2:3]
	v_cvt_pk_bf16_f32 v113, v114, v115
	v_max_f32_e32 v114, v124, v124
	v_max_f32_e32 v115, v125, v125
	v_cvt_pk_bf16_f32 v97, v98, v99
	v_max_f32_e32 v98, v108, v108
	v_max_f32_e32 v99, v109, v109
	v_cvt_pk_bf16_f32 v81, v82, v83
	v_max_f32_e32 v82, v92, v92
	v_max_f32_e32 v83, v93, v93
	v_cvt_pk_bf16_f32 v65, v66, v67
	v_max_f32_e32 v66, v76, v76
	v_max_f32_e32 v67, v77, v77
	v_cvt_pk_bf16_f32 v49, v50, v51
	v_max_f32_e32 v50, v60, v60
	v_max_f32_e32 v51, v61, v61
	v_cvt_pk_bf16_f32 v33, v34, v35
	v_max_f32_e32 v34, v44, v44
	v_max_f32_e32 v35, v45, v45
	v_cvt_pk_bf16_f32 v17, v18, v19
	v_max_f32_e32 v18, v28, v28
	v_max_f32_e32 v19, v29, v29
	v_cvt_pk_bf16_f32 v1, v2, v3
	v_max_f32_e32 v2, v12, v12
	v_max_f32_e32 v3, v13, v13
	v_max_f32_e32 v114, 0, v114
	v_max_f32_e32 v115, 0, v115
	v_max_f32_e32 v98, 0, v98
	v_max_f32_e32 v99, 0, v99
	v_max_f32_e32 v82, 0, v82
	v_max_f32_e32 v83, 0, v83
	v_max_f32_e32 v66, 0, v66
	v_max_f32_e32 v67, 0, v67
	v_max_f32_e32 v50, 0, v50
	v_max_f32_e32 v51, 0, v51
	v_max_f32_e32 v34, 0, v34
	v_max_f32_e32 v35, 0, v35
	v_max_f32_e32 v18, 0, v18
; DI unsigned pk2(float a, float b) { f32x2 v = {a, b}; return __builtin_bit_cast(unsigned, __builtin_convertvector(v, bf16x2_t)); }
;   DI static float act(float v) { const float t = fmaxf(v, 0.f); return t * t; }
; template <class Epi>
; DI void gemm_phase512(const bf16_t* A, const bf16_t* Bt, int mtiles, int ntiles, int K, int Kper, int ksplit, const Epi& epi,
;                       unsigned char* smem, int bid, int nb) {
;     ...
;         for (int ni = 0; ni < 2; ++ni)
; #pragma unroll
;           for (int mi = 0; mi < 4; ++mi)
; #pragma unroll
;             for (int g = 0; g < 4; ++g) {
;               u32x2 w;
;               w[0] = pk2(Epi::act(acc[ni][mi][4 * g]), Epi::act(acc[ni][mi][4 * g + 1]));
;               w[1] = pk2(Epi::act(acc[ni][mi][4 * g + 2]), Epi::act(acc[ni][mi][4 * g + 3]));
;               *(u32x2*)(wl + (mi * 32 + l31) * LDS_STRIDE + (ni * 32 + 8 * g + 4 * hh) * 2) = w;
;             }
;         asm volatile("" ::: "memory");
; #pragma unroll
;         for (int i = 0; i < 16; ++i) {
;           const int row = (lane >> 3) + 8 * i, ch = lane & 7;
;           const u32x4 w = *(const u32x4*)(wl + row * LDS_STRIDE + ch * 16);
;           *(u32x4*)(epi.O + (size_t)(m0 + row) * epi.ldc + n0 + ch * 8) = w;
;         }
	v_max_f32_e32 v19, 0, v19
	v_max_f32_e32 v2, 0, v2
	v_max_f32_e32 v3, 0, v3
	v_pk_mul_f32 v[114:115], v[114:115], v[114:115]
	v_pk_mul_f32 v[98:99], v[98:99], v[98:99]
	v_pk_mul_f32 v[82:83], v[82:83], v[82:83]
	v_pk_mul_f32 v[66:67], v[66:67], v[66:67]
	v_pk_mul_f32 v[50:51], v[50:51], v[50:51]
	v_pk_mul_f32 v[34:35], v[34:35], v[34:35]
	v_pk_mul_f32 v[18:19], v[18:19], v[18:19]
	v_pk_mul_f32 v[2:3], v[2:3], v[2:3]
	v_cvt_pk_bf16_f32 v114, v114, v115
	v_max_f32_e32 v115, v126, v126
	v_cvt_pk_bf16_f32 v98, v98, v99
	v_max_f32_e32 v99, v110, v110
	v_cvt_pk_bf16_f32 v82, v82, v83
	v_max_f32_e32 v83, v94, v94
	v_cvt_pk_bf16_f32 v66, v66, v67
	v_max_f32_e32 v67, v78, v78
	v_cvt_pk_bf16_f32 v50, v50, v51
	v_max_f32_e32 v51, v62, v62
	v_cvt_pk_bf16_f32 v34, v34, v35
	v_max_f32_e32 v35, v46, v46
	v_cvt_pk_bf16_f32 v18, v18, v19
	v_max_f32_e32 v19, v30, v30
	v_cvt_pk_bf16_f32 v2, v2, v3
	v_max_f32_e32 v3, v14, v14
	v_max_f32_e32 v116, 0, v115
	v_max_f32_e32 v115, v127, v127
	v_max_f32_e32 v100, 0, v99
	v_max_f32_e32 v99, v111, v111
	v_max_f32_e32 v84, 0, v83
	v_max_f32_e32 v83, v95, v95
	v_max_f32_e32 v68, 0, v67
	v_max_f32_e32 v67, v79, v79
	v_max_f32_e32 v52, 0, v51
	v_max_f32_e32 v51, v63, v63
	v_max_f32_e32 v36, 0, v35
	v_max_f32_e32 v35, v47, v47
	v_max_f32_e32 v20, 0, v19
	v_max_f32_e32 v19, v31, v31
	v_max_f32_e32 v4, 0, v3
	v_max_f32_e32 v3, v15, v15
	v_max_f32_e32 v117, 0, v115
	v_max_f32_e32 v101, 0, v99
	v_max_f32_e32 v85, 0, v83
	v_max_f32_e32 v69, 0, v67
	v_max_f32_e32 v53, 0, v51
	v_max_f32_e32 v37, 0, v35
	v_max_f32_e32 v21, 0, v19
	v_max_f32_e32 v5, 0, v3
	v_pk_mul_f32 v[116:117], v[116:117], v[116:117]
	v_pk_mul_f32 v[100:101], v[100:101], v[100:101]
	v_pk_mul_f32 v[84:85], v[84:85], v[84:85]
	v_pk_mul_f32 v[68:69], v[68:69], v[68:69]
	v_pk_mul_f32 v[52:53], v[52:53], v[52:53]
	v_pk_mul_f32 v[36:37], v[36:37], v[36:37]
	v_pk_mul_f32 v[20:21], v[20:21], v[20:21]
	v_pk_mul_f32 v[4:5], v[4:5], v[4:5]
	v_cvt_pk_bf16_f32 v115, v116, v117
	v_cvt_pk_bf16_f32 v99, v100, v101
	v_cvt_pk_bf16_f32 v83, v84, v85
	v_cvt_pk_bf16_f32 v67, v68, v69
	v_cvt_pk_bf16_f32 v51, v52, v53
	v_cvt_pk_bf16_f32 v35, v36, v37
	v_cvt_pk_bf16_f32 v19, v20, v21
	v_cvt_pk_bf16_f32 v3, v4, v5
	ds_write2_b64 v197, v[112:113], v[114:115] offset0:4 offset1:6
	ds_write2_b64 v102, v[96:97], v[98:99] offset0:68 offset1:70
	ds_write2_b64 v86, v[80:81], v[82:83] offset0:132 offset1:134
	ds_write2_b64 v70, v[64:65], v[66:67] offset0:196 offset1:198
	ds_write2_b64 v197, v[48:49], v[50:51] offset0:12 offset1:14
	ds_write2_b64 v102, v[32:33], v[34:35] offset0:76 offset1:78
	ds_write2_b64 v86, v[16:17], v[18:19] offset0:140 offset1:142
	ds_write2_b64 v70, v[0:1], v[2:3] offset0:204 offset1:206
	v_lshl_add_u32 v0, s25, 8, v173
	v_ashrrev_i32_e32 v1, 31, v0
	v_lshl_or_b32 v12, s26, 8, v174
	v_lshl_add_u64 v[8:9], v[0:1], 1, v[166:167]
	v_or_b32_e32 v4, v12, v175
	v_ashrrev_i32_e32 v5, 31, v4
	v_lshlrev_b64 v[4:5], 13, v[4:5]
	v_lshl_add_u64 v[10:11], v[8:9], 0, v[4:5]
	s_mov_b32 s100, 0x10000
	s_mov_b32 s101, 0
	ds_read_b128 v[16:19], v198
	ds_read_b128 v[20:23], v198 offset:1152
	ds_read_b128 v[24:27], v198 offset:2304
	ds_read_b128 v[28:31], v198 offset:3456
	ds_read_b128 v[32:35], v198 offset:4608
	ds_read_b128 v[36:39], v198 offset:5760
	ds_read_b128 v[40:43], v198 offset:6912
	ds_read_b128 v[44:47], v198 offset:8064
	s_waitcnt lgkmcnt(7)
	global_store_dwordx4 v[10:11], v[16:19], off
	v_lshl_add_u64 v[10:11], v[10:11], 0, s[100:101]
	ds_read_b128 v[48:51], v198 offset:9216
	s_waitcnt lgkmcnt(7)
	global_store_dwordx4 v[10:11], v[20:23], off
	v_lshl_add_u64 v[10:11], v[10:11], 0, s[100:101]
	ds_read_b128 v[52:55], v198 offset:10368
	s_waitcnt lgkmcnt(7)
	global_store_dwordx4 v[10:11], v[24:27], off
	v_lshl_add_u64 v[10:11], v[10:11], 0, s[100:101]
	ds_read_b128 v[56:59], v198 offset:11520
	s_waitcnt lgkmcnt(7)
	global_store_dwordx4 v[10:11], v[28:31], off
	v_lshl_add_u64 v[10:11], v[10:11], 0, s[100:101]
	ds_read_b128 v[60:63], v198 offset:12672
	s_waitcnt lgkmcnt(7)
	global_store_dwordx4 v[10:11], v[32:35], off
	v_lshl_add_u64 v[10:11], v[10:11], 0, s[100:101]
	ds_read_b128 v[64:67], v198 offset:13824
	s_waitcnt lgkmcnt(7)
	global_store_dwordx4 v[10:11], v[36:39], off
	v_lshl_add_u64 v[10:11], v[10:11], 0, s[100:101]
	ds_read_b128 v[68:71], v198 offset:14976
	s_waitcnt lgkmcnt(7)
	global_store_dwordx4 v[10:11], v[40:43], off
	v_lshl_add_u64 v[10:11], v[10:11], 0, s[100:101]
	ds_read_b128 v[72:75], v198 offset:16128
	s_waitcnt lgkmcnt(7)
	global_store_dwordx4 v[10:11], v[44:47], off
	v_lshl_add_u64 v[10:11], v[10:11], 0, s[100:101]
	ds_read_b128 v[76:79], v198 offset:17280
	s_waitcnt lgkmcnt(7)
	global_store_dwordx4 v[10:11], v[48:51], off
	v_lshl_add_u64 v[10:11], v[10:11], 0, s[100:101]
	s_waitcnt lgkmcnt(6)
	global_store_dwordx4 v[10:11], v[52:55], off
	v_lshl_add_u64 v[10:11], v[10:11], 0, s[100:101]
	s_waitcnt lgkmcnt(5)
	global_store_dwordx4 v[10:11], v[56:59], off
	v_lshl_add_u64 v[10:11], v[10:11], 0, s[100:101]
	s_waitcnt lgkmcnt(4)
	global_store_dwordx4 v[10:11], v[60:63], off
	v_lshl_add_u64 v[10:11], v[10:11], 0, s[100:101]
	s_waitcnt lgkmcnt(3)
	global_store_dwordx4 v[10:11], v[64:67], off
	v_lshl_add_u64 v[10:11], v[10:11], 0, s[100:101]
	s_waitcnt lgkmcnt(2)
	global_store_dwordx4 v[10:11], v[68:71], off
	v_lshl_add_u64 v[10:11], v[10:11], 0, s[100:101]
	s_waitcnt lgkmcnt(1)
	global_store_dwordx4 v[10:11], v[72:75], off
	v_lshl_add_u64 v[10:11], v[10:11], 0, s[100:101]
	s_waitcnt lgkmcnt(0)
	global_store_dwordx4 v[10:11], v[76:79], off
	s_mov_b32 s25, s22
	s_mov_b32 s26, s27
	s_barrier
	s_cbranch_vccz .LBB0_707
